# grid barrier between group-0 final norm and group-1 init removed (both phases touch only the calling wave's own rows)
# speedup vs baseline: 1.0036x; 1.0036x over previous
; __global__ void __launch_bounds__(512, 2) fwd_kernel(Params p) {
;     ...
;         if (grp == 1) { init_phase(xin, H, SS, NTOK); xcd_barrier(xbar); }
;     ...
;         final_norm_phase(H, p.in[4], xo, NTOK);
;         if (grp == 0) xcd_barrier(xbar);
.LBB0_1231:
	s_or_b64 exec, exec, s[10:11]
	v_readlane_b32 s0, v254, 17
	v_readlane_b32 s1, v254, 18
	s_mov_b64 s[6:7], -1
	s_and_b64 vcc, exec, s[0:1]
	s_mov_b64 s[10:11], -1
	s_cbranch_vccz .LBB0_218
	s_mov_b64 s[10:11], 0
	s_branch .LBB0_218
	s_waitcnt vmcnt(0)
	s_barrier
	s_mov_b64 s[10:11], exec
	v_readlane_b32 s0, v252, 2
	v_readlane_b32 s1, v252, 3
	s_and_b64 s[0:1], s[10:11], s[0:1]
	s_mov_b64 exec, s[0:1]
	s_cbranch_execz .LBB0_217
	v_readlane_b32 s0, v254, 6
	s_waitcnt vmcnt(0) expcnt(0) lgkmcnt(0)
	s_nop 0
	v_mov_b32_e32 v0, s0
	ds_read_b32 v3, v0
	v_readlane_b32 s0, v254, 7
	s_waitcnt lgkmcnt(0)
	v_cmp_ne_u32_e32 vcc, 0, v3
	v_mov_b32_e32 v0, s0
	ds_read_b32 v2, v0
	s_cbranch_vccnz .LBB0_1248
	s_mov_b32 s0, 1
	s_branch .LBB0_1236
